# v6 + GEMM9 tile-sync: drop redundant per-wave cache invalidate (partner partials are read with sc1 coherent loads)
# speedup vs baseline: 1.0254x; 1.0254x over previous
;     __device__ __forceinline__ void operator()(const f32x4 (&acc_)[2][2][4][2], const pg8::Unit& u, int wr, int wc, int fr, int fq) const {
;     ...
;         __builtin_amdgcn_fence(__ATOMIC_ACQUIRE, "agent");
;         asm volatile("s_waitcnt vmcnt(0)" ::: "memory");
;         f32x4 g[2][2];
; #pragma unroll
;         for (int bj = 0; bj < 2; ++bj) { g[bj][0] = *(const f32x4*)(gain + col0 + bj * 128); g[bj][1] = *(const f32x4*)(gain + col0 + bj * 128 + 4); }
; #pragma unroll
;         for (int ai = 0; ai < 2; ++ai)
; #pragma unroll
;             for (int m = 0; m < 4; ++m) {
;                 const int row = row0 + ai * 128 + m * 16; const float* xp = xch + (size_t)row * 16 + 4 * fq;
;                 float s = (__hip_atomic_load(xp + 0, __ATOMIC_RELAXED, __HIP_MEMORY_SCOPE_AGENT) + __hip_atomic_load(xp + 1, __ATOMIC_RELAXED, __HIP_MEMORY_SCOPE_AGENT))
;                         + (__hip_atomic_load(xp + 2, __ATOMIC_RELAXED, __HIP_MEMORY_SCOPE_AGENT) + __hip_atomic_load(xp + 3, __ATOMIC_RELAXED, __HIP_MEMORY_SCOPE_AGENT));
;                 s += __shfl_xor(s, 16); s += __shfl_xor(s, 32);
;                 const float rstd = __builtin_amdgcn_rsqf(s * (1.0f / 1024.0f) + EPS);
; #pragma unroll
;                 for (int bj = 0; bj < 2; ++bj) { const size_t off = (size_t)row * D + col0 + bj * 128;
;                     *(f32x4*)(out + off) = A[ai][bj][m][0] * rstd * g[bj][0]; *(f32x4*)(out + off + 4) = A[ai][bj][m][1] * rstd * g[bj][1]; }
;             }
.LBB0_982:
	v_lshlrev_b64 v[148:149], 2, v[148:149]
	s_waitcnt vmcnt(0)
	v_lshl_add_u64 v[8:9], s[24:25], 0, v[148:149]
	v_lshl_add_u64 v[156:157], v[136:137], 0, v[156:157]
	global_load_dwordx4 v[4:7], v[8:9], off offset:16
	global_load_dwordx4 v[12:15], v[8:9], off
	global_load_dwordx4 v[0:3], v[8:9], off offset:528
	s_nop 0
	global_load_dwordx4 v[8:11], v[8:9], off offset:512
	s_nop 0
	global_load_dword v208, v[156:157], off sc1
	global_load_dword v210, v[156:157], off offset:4 sc1
	global_load_dword v209, v[156:157], off offset:8 sc1
	global_load_dword v211, v[156:157], off offset:12 sc1
	v_lshlrev_b64 v[146:147], 12, v[146:147]
	v_lshl_add_u64 v[146:147], s[8:9], 0, v[146:147]
	v_lshl_add_u64 v[146:147], v[146:147], 0, v[148:149]
	v_lshl_add_u64 v[160:161], v[136:137], 0, v[160:161]
	global_load_dword v214, v[160:161], off sc1
	global_load_dword v216, v[160:161], off offset:4 sc1
	global_load_dword v215, v[160:161], off offset:8 sc1
	global_load_dword v217, v[160:161], off offset:12 sc1
	v_lshl_add_u64 v[242:243], v[136:137], 0, v[164:165]
	global_load_dword v218, v[242:243], off sc1
	global_load_dword v220, v[242:243], off offset:4 sc1
	global_load_dword v219, v[242:243], off offset:8 sc1
	global_load_dword v221, v[242:243], off offset:12 sc1
	v_lshl_add_u64 v[244:245], v[136:137], 0, v[168:169]
	global_load_dword v222, v[244:245], off sc1
	global_load_dword v224, v[244:245], off offset:4 sc1
	global_load_dword v223, v[244:245], off offset:8 sc1
	global_load_dword v225, v[244:245], off offset:12 sc1
	v_lshl_add_u64 v[242:243], v[136:137], 0, v[186:187]
	global_load_dword v226, v[242:243], off sc1
	global_load_dword v228, v[242:243], off offset:4 sc1
	global_load_dword v227, v[242:243], off offset:8 sc1
	global_load_dword v229, v[242:243], off offset:12 sc1
	v_lshl_add_u64 v[244:245], v[136:137], 0, v[190:191]
	global_load_dword v230, v[244:245], off sc1
	global_load_dword v232, v[244:245], off offset:4 sc1
	global_load_dword v231, v[244:245], off offset:8 sc1
	global_load_dword v233, v[244:245], off offset:12 sc1
	v_lshl_add_u64 v[242:243], v[136:137], 0, v[192:193]
	global_load_dword v234, v[242:243], off sc1
	global_load_dword v236, v[242:243], off offset:4 sc1
	global_load_dword v235, v[242:243], off offset:8 sc1
	global_load_dword v237, v[242:243], off offset:12 sc1
	v_lshl_add_u64 v[244:245], v[136:137], 0, v[194:195]
	global_load_dword v238, v[244:245], off sc1
	global_load_dword v240, v[244:245], off offset:4 sc1
	global_load_dword v239, v[244:245], off offset:8 sc1
	global_load_dword v241, v[244:245], off offset:12 sc1
	s_and_b64 vcc, exec, s[4:5]
	s_mov_b64 s[4:5], -1
	s_waitcnt vmcnt(0)
	v_pk_add_f32 v[156:157], v[208:209], v[210:211]
	s_nop 0
	v_add_f32_e32 v156, v156, v157
	ds_bpermute_b32 v157, v205, v156
	s_waitcnt lgkmcnt(0)
	v_add_f32_e32 v156, v156, v157
	ds_bpermute_b32 v157, v206, v156
	s_waitcnt lgkmcnt(0)
	v_add_f32_e32 v156, v156, v157
	v_fmamk_f32 v156, v156, 0x3a800000, v204
	v_rsq_f32_e32 v156, v156
	s_nop 0
	v_pk_mul_f32 v[124:125], v[124:125], v[156:157] op_sel_hi:[1,0]
	v_pk_mul_f32 v[126:127], v[126:127], v[156:157] op_sel_hi:[1,0]
	v_pk_mul_f32 v[120:121], v[120:121], v[156:157] op_sel_hi:[1,0]
	v_pk_mul_f32 v[122:123], v[122:123], v[156:157] op_sel_hi:[1,0]
	v_pk_mul_f32 v[208:209], v[116:117], v[156:157] op_sel_hi:[1,0]
	v_pk_mul_f32 v[210:211], v[118:119], v[156:157] op_sel_hi:[1,0]
	v_pk_mul_f32 v[212:213], v[112:113], v[156:157] op_sel_hi:[1,0]
	v_pk_mul_f32 v[156:157], v[114:115], v[156:157] op_sel_hi:[1,0]
	v_pk_mul_f32 v[114:115], v[14:15], v[126:127]
	v_pk_mul_f32 v[112:113], v[12:13], v[124:125]
	v_pk_mul_f32 v[118:119], v[6:7], v[122:123]
	v_pk_mul_f32 v[116:117], v[4:5], v[120:121]
	v_pk_mul_f32 v[122:123], v[10:11], v[210:211]
	v_pk_mul_f32 v[120:121], v[8:9], v[208:209]
	v_pk_mul_f32 v[126:127], v[2:3], v[156:157]
	v_pk_mul_f32 v[124:125], v[0:1], v[212:213]
	global_store_dwordx4 v[146:147], v[112:115], off
	global_store_dwordx4 v[146:147], v[116:119], off offset:16
	global_store_dwordx4 v[146:147], v[120:123], off offset:512
	global_store_dwordx4 v[146:147], v[124:127], off offset:528
	v_pk_add_f32 v[112:113], v[214:215], v[216:217]
	s_nop 0
	v_add_f32_e32 v112, v112, v113
	ds_bpermute_b32 v113, v205, v112
	s_waitcnt lgkmcnt(0)
	v_add_f32_e32 v114, v112, v113
	ds_bpermute_b32 v115, v206, v114
	v_lshlrev_b64 v[112:113], 12, v[150:151]
	v_lshl_add_u64 v[112:113], s[8:9], 0, v[112:113]
	v_lshl_add_u64 v[112:113], v[112:113], 0, v[148:149]
	s_waitcnt lgkmcnt(0)
	v_add_f32_e32 v114, v114, v115
	v_fmamk_f32 v114, v114, 0x3a800000, v204
	v_rsq_f32_e32 v114, v114
	s_nop 0
	v_pk_mul_f32 v[108:109], v[108:109], v[114:115] op_sel_hi:[1,0]
	v_pk_mul_f32 v[110:111], v[110:111], v[114:115] op_sel_hi:[1,0]
	v_pk_mul_f32 v[104:105], v[104:105], v[114:115] op_sel_hi:[1,0]
	v_pk_mul_f32 v[106:107], v[106:107], v[114:115] op_sel_hi:[1,0]
	v_pk_mul_f32 v[118:119], v[100:101], v[114:115] op_sel_hi:[1,0]
	v_pk_mul_f32 v[120:121], v[102:103], v[114:115] op_sel_hi:[1,0]
	v_pk_mul_f32 v[122:123], v[96:97], v[114:115] op_sel_hi:[1,0]
	v_pk_mul_f32 v[114:115], v[98:99], v[114:115] op_sel_hi:[1,0]
	v_pk_mul_f32 v[98:99], v[14:15], v[110:111]
	v_pk_mul_f32 v[96:97], v[12:13], v[108:109]
	v_pk_mul_f32 v[102:103], v[6:7], v[106:107]
	v_pk_mul_f32 v[100:101], v[4:5], v[104:105]
	v_pk_mul_f32 v[106:107], v[10:11], v[120:121]
	v_pk_mul_f32 v[104:105], v[8:9], v[118:119]
	v_pk_mul_f32 v[110:111], v[2:3], v[114:115]
	v_pk_mul_f32 v[108:109], v[0:1], v[122:123]
	global_store_dwordx4 v[112:113], v[96:99], off
	global_store_dwordx4 v[112:113], v[100:103], off offset:16
	global_store_dwordx4 v[112:113], v[104:107], off offset:512
	global_store_dwordx4 v[112:113], v[108:111], off offset:528
	v_pk_add_f32 v[96:97], v[218:219], v[220:221]
	s_nop 0
	v_add_f32_e32 v96, v96, v97
	ds_bpermute_b32 v97, v205, v96
	s_waitcnt lgkmcnt(0)
;     __device__ __forceinline__ void operator()(const f32x4 (&acc_)[2][2][4][2], const pg8::Unit& u, int wr, int wc, int fr, int fq) const {
;     ...
;         for (int ai = 0; ai < 2; ++ai)
; #pragma unroll
;             for (int m = 0; m < 4; ++m) {
;                 const int row = row0 + ai * 128 + m * 16; const float* xp = xch + (size_t)row * 16 + 4 * fq;
;                 float s = (__hip_atomic_load(xp + 0, __ATOMIC_RELAXED, __HIP_MEMORY_SCOPE_AGENT) + __hip_atomic_load(xp + 1, __ATOMIC_RELAXED, __HIP_MEMORY_SCOPE_AGENT))
;                         + (__hip_atomic_load(xp + 2, __ATOMIC_RELAXED, __HIP_MEMORY_SCOPE_AGENT) + __hip_atomic_load(xp + 3, __ATOMIC_RELAXED, __HIP_MEMORY_SCOPE_AGENT));
;                 s += __shfl_xor(s, 16); s += __shfl_xor(s, 32);
;                 const float rstd = __builtin_amdgcn_rsqf(s * (1.0f / 1024.0f) + EPS);
; #pragma unroll
;                 for (int bj = 0; bj < 2; ++bj) { const size_t off = (size_t)row * D + col0 + bj * 128;
;                     *(f32x4*)(out + off) = A[ai][bj][m][0] * rstd * g[bj][0]; *(f32x4*)(out + off + 4) = A[ai][bj][m][1] * rstd * g[bj][1]; }
;             }
	v_add_f32_e32 v98, v96, v97
	ds_bpermute_b32 v99, v206, v98
	v_lshlrev_b64 v[96:97], 12, v[152:153]
	v_lshl_add_u64 v[96:97], s[8:9], 0, v[96:97]
	v_lshl_add_u64 v[96:97], v[96:97], 0, v[148:149]
	s_waitcnt lgkmcnt(0)
	v_add_f32_e32 v98, v98, v99
	v_fmamk_f32 v98, v98, 0x3a800000, v204
	v_rsq_f32_e32 v98, v98
	s_nop 0
	v_pk_mul_f32 v[92:93], v[92:93], v[98:99] op_sel_hi:[1,0]
	v_pk_mul_f32 v[94:95], v[94:95], v[98:99] op_sel_hi:[1,0]
	v_pk_mul_f32 v[88:89], v[88:89], v[98:99] op_sel_hi:[1,0]
	v_pk_mul_f32 v[90:91], v[90:91], v[98:99] op_sel_hi:[1,0]
	v_pk_mul_f32 v[102:103], v[84:85], v[98:99] op_sel_hi:[1,0]
	v_pk_mul_f32 v[104:105], v[86:87], v[98:99] op_sel_hi:[1,0]
	v_pk_mul_f32 v[106:107], v[80:81], v[98:99] op_sel_hi:[1,0]
	v_pk_mul_f32 v[98:99], v[82:83], v[98:99] op_sel_hi:[1,0]
	v_pk_mul_f32 v[82:83], v[14:15], v[94:95]
	v_pk_mul_f32 v[80:81], v[12:13], v[92:93]
	v_pk_mul_f32 v[86:87], v[6:7], v[90:91]
	v_pk_mul_f32 v[84:85], v[4:5], v[88:89]
	v_pk_mul_f32 v[90:91], v[10:11], v[104:105]
	v_pk_mul_f32 v[88:89], v[8:9], v[102:103]
	v_pk_mul_f32 v[94:95], v[2:3], v[98:99]
	v_pk_mul_f32 v[92:93], v[0:1], v[106:107]
	global_store_dwordx4 v[96:97], v[80:83], off
	global_store_dwordx4 v[96:97], v[84:87], off offset:16
	global_store_dwordx4 v[96:97], v[88:91], off offset:512
	global_store_dwordx4 v[96:97], v[92:95], off offset:528
	v_pk_add_f32 v[80:81], v[222:223], v[224:225]
	s_nop 0
	v_add_f32_e32 v80, v80, v81
	ds_bpermute_b32 v81, v205, v80
	s_waitcnt lgkmcnt(0)
	v_add_f32_e32 v82, v80, v81
	ds_bpermute_b32 v83, v206, v82
	v_lshlrev_b64 v[80:81], 12, v[154:155]
	v_lshl_add_u64 v[80:81], s[8:9], 0, v[80:81]
	v_lshl_add_u64 v[80:81], v[80:81], 0, v[148:149]
	s_waitcnt lgkmcnt(0)
	v_add_f32_e32 v82, v82, v83
	v_fmamk_f32 v82, v82, 0x3a800000, v204
	v_rsq_f32_e32 v82, v82
	s_nop 0
	v_pk_mul_f32 v[76:77], v[76:77], v[82:83] op_sel_hi:[1,0]
	v_pk_mul_f32 v[78:79], v[78:79], v[82:83] op_sel_hi:[1,0]
	v_pk_mul_f32 v[72:73], v[72:73], v[82:83] op_sel_hi:[1,0]
	v_pk_mul_f32 v[74:75], v[74:75], v[82:83] op_sel_hi:[1,0]
	v_pk_mul_f32 v[86:87], v[68:69], v[82:83] op_sel_hi:[1,0]
	v_pk_mul_f32 v[88:89], v[70:71], v[82:83] op_sel_hi:[1,0]
	v_pk_mul_f32 v[90:91], v[64:65], v[82:83] op_sel_hi:[1,0]
	v_pk_mul_f32 v[82:83], v[66:67], v[82:83] op_sel_hi:[1,0]
	v_pk_mul_f32 v[66:67], v[14:15], v[78:79]
	v_pk_mul_f32 v[64:65], v[12:13], v[76:77]
	v_pk_mul_f32 v[70:71], v[6:7], v[74:75]
	v_pk_mul_f32 v[68:69], v[4:5], v[72:73]
	v_pk_mul_f32 v[74:75], v[10:11], v[88:89]
	v_pk_mul_f32 v[72:73], v[8:9], v[86:87]
	v_pk_mul_f32 v[78:79], v[2:3], v[82:83]
	v_pk_mul_f32 v[76:77], v[0:1], v[90:91]
	global_store_dwordx4 v[80:81], v[64:67], off
	global_store_dwordx4 v[80:81], v[68:71], off offset:16
	global_store_dwordx4 v[80:81], v[72:75], off offset:512
	global_store_dwordx4 v[80:81], v[76:79], off offset:528
	v_pk_add_f32 v[64:65], v[226:227], v[228:229]
	s_nop 0
	v_add_f32_e32 v64, v64, v65
	ds_bpermute_b32 v65, v205, v64
	s_waitcnt lgkmcnt(0)
	v_add_f32_e32 v66, v64, v65
	ds_bpermute_b32 v67, v206, v66
	v_lshlrev_b64 v[64:65], 12, v[158:159]
	v_lshl_add_u64 v[64:65], s[8:9], 0, v[64:65]
	v_lshl_add_u64 v[64:65], v[64:65], 0, v[148:149]
	s_waitcnt lgkmcnt(0)
	v_add_f32_e32 v66, v66, v67
	v_fmamk_f32 v66, v66, 0x3a800000, v204
	v_rsq_f32_e32 v66, v66
	s_nop 0
	v_pk_mul_f32 v[60:61], v[60:61], v[66:67] op_sel_hi:[1,0]
	v_pk_mul_f32 v[62:63], v[62:63], v[66:67] op_sel_hi:[1,0]
	v_pk_mul_f32 v[56:57], v[56:57], v[66:67] op_sel_hi:[1,0]
	v_pk_mul_f32 v[58:59], v[58:59], v[66:67] op_sel_hi:[1,0]
	v_pk_mul_f32 v[70:71], v[52:53], v[66:67] op_sel_hi:[1,0]
	v_pk_mul_f32 v[72:73], v[54:55], v[66:67] op_sel_hi:[1,0]
	v_pk_mul_f32 v[74:75], v[48:49], v[66:67] op_sel_hi:[1,0]
	v_pk_mul_f32 v[66:67], v[50:51], v[66:67] op_sel_hi:[1,0]
	v_pk_mul_f32 v[50:51], v[14:15], v[62:63]
	v_pk_mul_f32 v[48:49], v[12:13], v[60:61]
	v_pk_mul_f32 v[54:55], v[6:7], v[58:59]
	v_pk_mul_f32 v[52:53], v[4:5], v[56:57]
	v_pk_mul_f32 v[58:59], v[10:11], v[72:73]
	v_pk_mul_f32 v[56:57], v[8:9], v[70:71]
	v_pk_mul_f32 v[62:63], v[2:3], v[66:67]
	v_pk_mul_f32 v[60:61], v[0:1], v[74:75]
	global_store_dwordx4 v[64:65], v[48:51], off
	global_store_dwordx4 v[64:65], v[52:55], off offset:16
	global_store_dwordx4 v[64:65], v[56:59], off offset:512
	global_store_dwordx4 v[64:65], v[60:63], off offset:528
	v_pk_add_f32 v[48:49], v[230:231], v[232:233]
	s_nop 0
	v_add_f32_e32 v48, v48, v49
	ds_bpermute_b32 v49, v205, v48
	s_waitcnt lgkmcnt(0)
;     __device__ __forceinline__ void operator()(const f32x4 (&acc_)[2][2][4][2], const pg8::Unit& u, int wr, int wc, int fr, int fq) const {
;     ...
;         for (int ai = 0; ai < 2; ++ai)
; #pragma unroll
;             for (int m = 0; m < 4; ++m) {
;                 const int row = row0 + ai * 128 + m * 16; const float* xp = xch + (size_t)row * 16 + 4 * fq;
;                 float s = (__hip_atomic_load(xp + 0, __ATOMIC_RELAXED, __HIP_MEMORY_SCOPE_AGENT) + __hip_atomic_load(xp + 1, __ATOMIC_RELAXED, __HIP_MEMORY_SCOPE_AGENT))
;                         + (__hip_atomic_load(xp + 2, __ATOMIC_RELAXED, __HIP_MEMORY_SCOPE_AGENT) + __hip_atomic_load(xp + 3, __ATOMIC_RELAXED, __HIP_MEMORY_SCOPE_AGENT));
;                 s += __shfl_xor(s, 16); s += __shfl_xor(s, 32);
;                 const float rstd = __builtin_amdgcn_rsqf(s * (1.0f / 1024.0f) + EPS);
; #pragma unroll
;                 for (int bj = 0; bj < 2; ++bj) { const size_t off = (size_t)row * D + col0 + bj * 128;
;                     *(f32x4*)(out + off) = A[ai][bj][m][0] * rstd * g[bj][0]; *(f32x4*)(out + off + 4) = A[ai][bj][m][1] * rstd * g[bj][1]; }
;             }
	v_add_f32_e32 v50, v48, v49
	ds_bpermute_b32 v51, v206, v50
	v_lshlrev_b64 v[48:49], 12, v[162:163]
	v_lshl_add_u64 v[48:49], s[8:9], 0, v[48:49]
	v_lshl_add_u64 v[48:49], v[48:49], 0, v[148:149]
	s_waitcnt lgkmcnt(0)
	v_add_f32_e32 v50, v50, v51
	v_fmamk_f32 v50, v50, 0x3a800000, v204
	v_rsq_f32_e32 v50, v50
	s_nop 0
	v_pk_mul_f32 v[44:45], v[44:45], v[50:51] op_sel_hi:[1,0]
	v_pk_mul_f32 v[46:47], v[46:47], v[50:51] op_sel_hi:[1,0]
	v_pk_mul_f32 v[40:41], v[40:41], v[50:51] op_sel_hi:[1,0]
	v_pk_mul_f32 v[42:43], v[42:43], v[50:51] op_sel_hi:[1,0]
	v_pk_mul_f32 v[54:55], v[36:37], v[50:51] op_sel_hi:[1,0]
	v_pk_mul_f32 v[56:57], v[38:39], v[50:51] op_sel_hi:[1,0]
	v_pk_mul_f32 v[58:59], v[32:33], v[50:51] op_sel_hi:[1,0]
	v_pk_mul_f32 v[50:51], v[34:35], v[50:51] op_sel_hi:[1,0]
	v_pk_mul_f32 v[34:35], v[14:15], v[46:47]
	v_pk_mul_f32 v[32:33], v[12:13], v[44:45]
	v_pk_mul_f32 v[38:39], v[6:7], v[42:43]
	v_pk_mul_f32 v[36:37], v[4:5], v[40:41]
	v_pk_mul_f32 v[42:43], v[10:11], v[56:57]
	v_pk_mul_f32 v[40:41], v[8:9], v[54:55]
	v_pk_mul_f32 v[46:47], v[2:3], v[50:51]
	v_pk_mul_f32 v[44:45], v[0:1], v[58:59]
	global_store_dwordx4 v[48:49], v[32:35], off
	global_store_dwordx4 v[48:49], v[36:39], off offset:16
	global_store_dwordx4 v[48:49], v[40:43], off offset:512
	global_store_dwordx4 v[48:49], v[44:47], off offset:528
	v_pk_add_f32 v[32:33], v[234:235], v[236:237]
	s_nop 0
	v_add_f32_e32 v32, v32, v33
	ds_bpermute_b32 v33, v205, v32
	s_waitcnt lgkmcnt(0)
	v_add_f32_e32 v34, v32, v33
	ds_bpermute_b32 v35, v206, v34
	v_lshlrev_b64 v[32:33], 12, v[166:167]
	v_lshl_add_u64 v[32:33], s[8:9], 0, v[32:33]
	v_lshl_add_u64 v[32:33], v[32:33], 0, v[148:149]
	s_waitcnt lgkmcnt(0)
	v_add_f32_e32 v34, v34, v35
	v_fmamk_f32 v34, v34, 0x3a800000, v204
	v_rsq_f32_e32 v34, v34
	s_nop 0
	v_pk_mul_f32 v[28:29], v[28:29], v[34:35] op_sel_hi:[1,0]
	v_pk_mul_f32 v[30:31], v[30:31], v[34:35] op_sel_hi:[1,0]
	v_pk_mul_f32 v[24:25], v[24:25], v[34:35] op_sel_hi:[1,0]
	v_pk_mul_f32 v[26:27], v[26:27], v[34:35] op_sel_hi:[1,0]
	v_pk_mul_f32 v[38:39], v[20:21], v[34:35] op_sel_hi:[1,0]
	v_pk_mul_f32 v[40:41], v[22:23], v[34:35] op_sel_hi:[1,0]
	v_pk_mul_f32 v[42:43], v[16:17], v[34:35] op_sel_hi:[1,0]
	v_pk_mul_f32 v[34:35], v[18:19], v[34:35] op_sel_hi:[1,0]
	v_pk_mul_f32 v[18:19], v[14:15], v[30:31]
	v_pk_mul_f32 v[16:17], v[12:13], v[28:29]
	v_pk_mul_f32 v[22:23], v[6:7], v[26:27]
	v_pk_mul_f32 v[20:21], v[4:5], v[24:25]
	v_pk_mul_f32 v[26:27], v[10:11], v[40:41]
	v_pk_mul_f32 v[24:25], v[8:9], v[38:39]
	v_pk_mul_f32 v[30:31], v[2:3], v[34:35]
	v_pk_mul_f32 v[28:29], v[0:1], v[42:43]
	global_store_dwordx4 v[32:33], v[16:19], off
	global_store_dwordx4 v[32:33], v[20:23], off offset:16
	global_store_dwordx4 v[32:33], v[24:27], off offset:512
	global_store_dwordx4 v[32:33], v[28:31], off offset:528
	v_pk_add_f32 v[16:17], v[238:239], v[240:241]
	s_nop 0
	v_add_f32_e32 v16, v16, v17
	ds_bpermute_b32 v17, v205, v16
	s_waitcnt lgkmcnt(0)
	v_add_f32_e32 v18, v16, v17
	ds_bpermute_b32 v19, v206, v18
	v_lshlrev_b64 v[16:17], 12, v[170:171]
	v_lshl_add_u64 v[16:17], s[8:9], 0, v[16:17]
	v_lshl_add_u64 v[16:17], v[16:17], 0, v[148:149]
	s_waitcnt lgkmcnt(0)
	v_add_f32_e32 v18, v18, v19
	v_fmamk_f32 v18, v18, 0x3a800000, v204
	v_rsq_f32_e32 v18, v18
	s_nop 0
	v_pk_mul_f32 v[20:21], v[178:179], v[18:19] op_sel_hi:[1,0]
	v_pk_mul_f32 v[22:23], v[174:175], v[18:19] op_sel_hi:[1,0]
	v_pk_mul_f32 v[24:25], v[176:177], v[18:19] op_sel_hi:[1,0]
	v_pk_mul_f32 v[26:27], v[172:173], v[18:19] op_sel_hi:[1,0]
	v_pk_mul_f32 v[28:29], v[182:183], v[18:19] op_sel_hi:[1,0]
	v_pk_mul_f32 v[30:31], v[180:181], v[18:19] op_sel_hi:[1,0]
	v_pk_mul_f32 v[32:33], v[188:189], v[18:19] op_sel_hi:[1,0]
	v_pk_mul_f32 v[18:19], v[184:185], v[18:19] op_sel_hi:[1,0]
	v_pk_mul_f32 v[14:15], v[14:15], v[22:23]
	v_pk_mul_f32 v[12:13], v[12:13], v[20:21]
	v_pk_mul_f32 v[6:7], v[6:7], v[26:27]
	v_pk_mul_f32 v[4:5], v[4:5], v[24:25]
	v_pk_mul_f32 v[10:11], v[10:11], v[30:31]
	v_pk_mul_f32 v[8:9], v[8:9], v[28:29]
	v_pk_mul_f32 v[2:3], v[2:3], v[18:19]
	v_pk_mul_f32 v[0:1], v[0:1], v[32:33]
	global_store_dwordx4 v[16:17], v[12:15], off
	global_store_dwordx4 v[16:17], v[4:7], off offset:16
	global_store_dwordx4 v[16:17], v[8:11], off offset:512
	global_store_dwordx4 v[16:17], v[0:3], off offset:528
	s_cbranch_vccnz .LBB0_948
	s_andn2_b64 vcc, exec, s[22:23]
	s_cbranch_vccnz .LBB0_947
	s_barrier
	s_branch .LBB0_947
